# combined: barrier-shadow sample pool items + barrier-shadow weight-tile prefetch on top of 64-bit zeroing
# speedup vs baseline: 1.0048x; 1.0011x over previous
; __device__ __forceinline__ unsigned xb_add(unsigned* p, unsigned v) { return __hip_atomic_fetch_add(p, v, __ATOMIC_RELAXED, __HIP_MEMORY_SCOPE_AGENT); }
; #define SEAM(k) do { if (IN(k) && IN((k) + 1)) xcd_barrier(bar); STAMP_IF((k) + 1); } while (0)
; #define SEAM(k) do { if (IN(k) && IN((k) + 1)) xcd_barrier(bar); } while (0)
; __device__ __forceinline__ void xcd_barrier(const XcdBarrier& b) {
;     asm volatile("s_waitcnt vmcnt(0)" ::: "memory");
;     __syncthreads();
;     if (threadIdx.x == 0) {
;         unsigned* bar = b.bar;
;         __builtin_amdgcn_s_waitcnt(0);
;         unsigned nloc = b.st[0], nx = b.st[1];
;         if (nloc == 0u) { xcd_barrier_complete(bar, b.x, nloc, nx); b.st[0] = nloc; b.st[1] = nx; }
;         const unsigned old = xb_add(&bar[XB_XSUB(b.x)], 1u);
; __global__ void __launch_bounds__(NWAVES * 64, 2) mk_fwd(Args args) {
;     ...
;     } SEAM(3);
;     if (IN(4)) {
;         pg8::Gemm g{F.MIX, F.WOUT, TP, D, D}; pg8::StaticOrder S; S.init(TP, D, F.G, (int)blockIdx.x);
.LBB0_704:
	s_cmp_gt_i32 s71, 4
	s_cselect_b64 s[0:1], -1, 0
	s_and_b64 s[2:3], s[40:41], s[0:1]
	s_andn2_b64 vcc, exec, s[2:3]
	s_cbranch_vccnz .LBB0_754
	s_waitcnt vmcnt(0)
	v_cmp_eq_u32_e32 vcc, 0, v0
	s_waitcnt vmcnt(0) lgkmcnt(0)
	s_barrier
	v_readfirstlane_b32 s56, v0
	s_cmp_lt_u32 s56, 64
	s_cbranch_scc1 .Lpfb_skip4
	s_lshr_b32 s57, s88, 6
	s_lshl_b32 s57, s57, 19
	v_readlane_b32 s60, v254, 19
	v_readlane_b32 s61, v254, 20
	s_add_u32 s60, s60, s57
	s_addc_u32 s61, s61, 0
	s_add_u32 s60, s60, 0x6fc000
	s_addc_u32 s61, s61, 0
	v_subrev_u32_e32 v162, 64, v0
	v_lshrrev_b32_e32 v163, 1, v162
	v_lshlrev_b32_e32 v163, 11, v163
	v_and_b32_e32 v164, 1, v162
	v_lshl_or_b32 v163, v164, 7, v163
	global_load_dword v165, v163, s[60:61]
	v_and_b32_e32 v162, 63, v162
	v_add_u32_e32 v162, 0x1c0, v162
	v_lshrrev_b32_e32 v166, 1, v162
	v_lshlrev_b32_e32 v166, 11, v166
	v_and_b32_e32 v164, 1, v162
	v_lshl_or_b32 v166, v164, 7, v166
	global_load_dword v167, v166, s[60:61]
.Lpfb_skip4:
	s_and_saveexec_b64 s[4:5], vcc
	s_cbranch_execz .LBB0_753
	v_readlane_b32 s2, v254, 22
	s_waitcnt vmcnt(0) expcnt(0) lgkmcnt(0)
	s_nop 0
	v_mov_b32_e32 v2, s2
	ds_read_b32 v4, v2
	ds_read_b32 v2, v2 offset:4
	s_waitcnt lgkmcnt(1)
	v_cmp_ne_u32_e32 vcc, 0, v4
	s_cbranch_vccnz .LBB0_721
	v_readlane_b32 s6, v254, 1
	v_readlane_b32 s7, v254, 2
	s_load_dwordx2 s[2:3], s[6:7], 0x4
	s_add_u32 s6, s68, 0x4200
	s_addc_u32 s7, s69, 0
	s_add_u32 s8, s68, 0x4400
	s_addc_u32 s9, s69, 0
	s_add_u32 s10, s68, 0x4500
	s_addc_u32 s11, s69, 0
	s_add_u32 s12, s68, 0x4600
	s_addc_u32 s13, s69, 0
	s_add_u32 s14, s68, 0x4700
	s_addc_u32 s15, s69, 0
	s_add_u32 s16, s68, 0x4800
	s_addc_u32 s17, s69, 0
	s_add_u32 s18, s68, 0x4900
	s_addc_u32 s19, s69, 0
	s_add_u32 s20, s68, 0x4a00
	s_addc_u32 s21, s69, 0
	s_add_u32 s22, s68, 0x4b00
	s_addc_u32 s23, s69, 0
	s_add_u32 s24, s68, 0x4c00
	s_addc_u32 s25, s69, 0
	s_add_u32 s26, s68, 0x4d00
	s_addc_u32 s27, s69, 0
	s_add_u32 s28, s68, 0x4e00
	s_addc_u32 s29, s69, 0
	s_add_u32 s30, s68, 0x4f00
	s_addc_u32 s31, s69, 0
	s_add_u32 s34, s68, 0x5000
	s_addc_u32 s35, s69, 0
	s_add_u32 s40, s68, 0x5100
	s_addc_u32 s41, s69, 0
	s_add_u32 s42, s68, 0x5200
	s_addc_u32 s43, s69, 0
	s_waitcnt lgkmcnt(0)
	s_mul_i32 s33, s2, s79
	s_add_u32 s44, s68, 0x5300
	s_mul_i32 s33, s33, s3
	s_addc_u32 s45, s69, 0
	s_mov_b32 s50, 1
	v_mov_b32_e32 v18, 0
	s_branch .LBB0_709

; __device__ __forceinline__ unsigned xb_add(unsigned* p, unsigned v) { return __hip_atomic_fetch_add(p, v, __ATOMIC_RELAXED, __HIP_MEMORY_SCOPE_AGENT); }
; __device__ __forceinline__ void xcd_barrier(const XcdBarrier& b) {
;     asm volatile("s_waitcnt vmcnt(0)" ::: "memory");
;     __syncthreads();
;     if (threadIdx.x == 0) {
;         unsigned* bar = b.bar;
;         __builtin_amdgcn_s_waitcnt(0);
;         unsigned nloc = b.st[0], nx = b.st[1];
;         if (nloc == 0u) { xcd_barrier_complete(bar, b.x, nloc, nx); b.st[0] = nloc; b.st[1] = nx; }
;         const unsigned old = xb_add(&bar[XB_XSUB(b.x)], 1u);
; __global__ void __launch_bounds__(NWAVES * 64, 2) mk_fwd(Args args) {
;     ...
;         pg8::Gemm g{F.XN, F.WUP, MT, 2 * DFF, D}; pg8::StaticOrder S; S.init(MT, 2 * DFF, F.G, (int)blockIdx.x);
.LBB0_801:
	s_cmp_gt_i32 s71, 5
	s_cselect_b64 s[0:1], -1, 0
	s_and_b64 s[2:3], s[6:7], s[0:1]
	v_readlane_b32 s56, v254, 42
	s_andn2_b64 vcc, exec, s[2:3]
	v_readlane_b32 s57, v254, 43
	s_cbranch_vccnz .LBB0_851
	s_waitcnt vmcnt(0)
	v_cmp_eq_u32_e32 vcc, 0, v0
	s_waitcnt vmcnt(0) lgkmcnt(0)
	s_barrier
	v_readfirstlane_b32 s90, v0
	s_cmp_lt_u32 s90, 64
	s_cbranch_scc1 .Lpfb_skip5
	s_and_b32 s91, s88, 7
	s_mul_i32 s91, s91, 11
	s_lshr_b32 s92, s88, 3
	s_add_i32 s91, s91, s92
	s_lshr_b32 s91, s91, 3
	s_lshl_b32 s91, s91, 19
	v_readlane_b32 s74, v254, 19
	v_readlane_b32 s75, v254, 20
	s_add_u32 s74, s74, s91
	s_addc_u32 s75, s75, 0
	s_add_u32 s74, s74, 0x8fc000
	s_addc_u32 s75, s75, 0
	v_subrev_u32_e32 v226, 64, v0
	v_lshrrev_b32_e32 v227, 1, v226
	v_lshlrev_b32_e32 v227, 11, v227
	v_and_b32_e32 v228, 1, v226
	v_lshl_or_b32 v227, v228, 7, v227
	global_load_dword v229, v227, s[74:75]
	v_and_b32_e32 v226, 63, v226
	v_add_u32_e32 v226, 0x1c0, v226
	v_lshrrev_b32_e32 v230, 1, v226
	v_lshlrev_b32_e32 v230, 11, v230
	v_and_b32_e32 v228, 1, v226
	v_lshl_or_b32 v230, v228, 7, v230
	global_load_dword v231, v230, s[74:75]
.Lpfb_skip5:
	s_and_saveexec_b64 s[4:5], vcc
	s_cbranch_execz .LBB0_850
	v_readlane_b32 s2, v254, 22
	s_waitcnt vmcnt(0) expcnt(0) lgkmcnt(0)
	s_nop 0
	v_mov_b32_e32 v2, s2
	ds_read_b32 v4, v2
	ds_read_b32 v2, v2 offset:4
	s_waitcnt lgkmcnt(1)
	v_cmp_ne_u32_e32 vcc, 0, v4
	s_cbranch_vccnz .LBB0_818
	v_readlane_b32 s6, v254, 1
	v_readlane_b32 s7, v254, 2
	s_load_dwordx2 s[2:3], s[6:7], 0x4
	s_add_u32 s6, s68, 0x4200
	s_addc_u32 s7, s69, 0
	s_add_u32 s8, s68, 0x4400
	s_addc_u32 s9, s69, 0
	s_add_u32 s10, s68, 0x4500
	s_addc_u32 s11, s69, 0
	s_add_u32 s12, s68, 0x4600
	s_addc_u32 s13, s69, 0
	s_add_u32 s14, s68, 0x4700
	s_addc_u32 s15, s69, 0
	s_add_u32 s16, s68, 0x4800
	s_addc_u32 s17, s69, 0
	s_add_u32 s18, s68, 0x4900
	s_addc_u32 s19, s69, 0
	s_add_u32 s24, s68, 0x4a00
	s_addc_u32 s25, s69, 0
	s_add_u32 s26, s68, 0x4b00
	s_addc_u32 s27, s69, 0
	s_add_u32 s28, s68, 0x4c00
	s_addc_u32 s29, s69, 0
	s_add_u32 s30, s68, 0x4d00
	s_addc_u32 s31, s69, 0
	s_add_u32 s34, s68, 0x4e00
	s_addc_u32 s35, s69, 0
	s_add_u32 s38, s68, 0x4f00
	s_addc_u32 s39, s69, 0
	s_add_u32 s40, s68, 0x5000
	s_addc_u32 s41, s69, 0
	s_add_u32 s42, s68, 0x5100
	s_addc_u32 s43, s69, 0
	s_add_u32 s44, s68, 0x5200
	s_addc_u32 s45, s69, 0
	s_waitcnt lgkmcnt(0)
	s_mul_i32 s33, s2, s79
	s_add_u32 s46, s68, 0x5300
	s_mul_i32 s33, s33, s3
	s_addc_u32 s47, s69, 0
	s_mov_b32 s52, 1
	v_mov_b32_e32 v18, 0
	s_branch .LBB0_806
